# v16-plus-P0-item-rebalance
# speedup vs baseline: 1.0027x; 1.0027x over previous
; __global__ void __launch_bounds__(NWAVES * 64, 2) mk_fwd(Args args) {
;     ...
;             for (int sl = (args.sub == 11 ? (1 << 30) : gw); sl < 2048; sl += NGW) {
;                 const int it = sl;
;                 if (sl < 1024) { if (args.sub < 13 || args.sub == 13) p0_s5_kitem(SP, MQ, it >> 4, 2 * (it & 7) + ((it >> 3) & 1), lane); }
;                 else if (sl < 2048) { if (args.sub < 13 || args.sub == 14) p0_s5_qitem(SP, MQ, (it - 1024) >> 4, it & 15, lane);
;                                       if (args.sub < 13 || args.sub == 15) p0_s5_pitem(SP, PT, A16, (it - 1024) >> 4, it & 15, lane); }
;             }
.LBB0_30:
	s_cmp_lg_u32 s94, 11
	s_cselect_b64 s[14:15], -1, 0
	s_and_b64 s[2:3], s[14:15], s[8:9]
	s_andn2_b64 vcc, exec, s[2:3]
	s_cbranch_vccnz .LBB0_54
	s_cmp_lt_i32 s94, 13
	s_cselect_b64 s[2:3], -1, 0
	s_cmp_eq_u32 s94, 14
	s_cselect_b64 s[4:5], -1, 0
	s_waitcnt lgkmcnt(0)
	s_or_b64 s[38:39], s[2:3], s[4:5]
	s_cmp_eq_u32 s94, 15
	s_cselect_b64 s[4:5], -1, 0
	v_lshrrev_b32_e32 v2, 2, v194
	s_or_b64 s[40:41], s[2:3], s[4:5]
	v_readlane_b32 s2, v234, 24
	v_and_b32_e32 v22, 15, v0
	v_and_b32_e32 v23, 12, v2
	v_or_b32_e32 v2, 3, v2
	v_lshlrev_b32_e32 v18, 9, v194
	v_mov_b32_e32 v19, 0
	v_readlane_b32 s3, v234, 25
	v_and_b32_e32 v1, 48, v0
	v_cmp_eq_u32_e64 s[8:9], v2, v22
	v_mbcnt_lo_u32_b32 v2, -1, 0
	v_lshl_add_u64 v[20:21], s[2:3], 0, v[18:19]
	s_cmp_lt_i32 s94, 14
	v_lshlrev_b32_e32 v18, 2, v1
	v_or_b32_e32 v3, 1, v23
	v_readlane_b32 s12, v234, 4
	v_mbcnt_hi_u32_b32 v2, -1, v2
	s_cselect_b64 s[62:63], -1, 0
	v_lshl_add_u64 v[24:25], s[24:25], 0, v[18:19]
	v_lshl_add_u64 v[26:27], s[26:27], 0, v[18:19]
	v_cmp_eq_u32_e64 s[4:5], v3, v22
	v_or_b32_e32 v3, 2, v23
	v_lshlrev_b32_e32 v18, 1, v194
	s_lshl_b32 s12, s12, 4
	s_lshl_b32 s13, s86, 1
	v_and_or_b32 v2, v2, 64, v1
	v_cmp_eq_u32_e64 s[2:3], v23, v22
	v_cmp_eq_u32_e64 s[6:7], v3, v22
	v_lshl_add_u64 v[28:29], s[68:69], 0, v[18:19]
	s_add_i32 s58, s12, s13
	s_lshl_b32 s59, s33, 4
	s_mov_b32 s65, 0
	s_mov_b32 s70, 0x3fb8aa3b
	s_mov_b32 s71, 0xc2ce8ed0
	s_mov_b32 s74, 0x42b17218
	s_movk_i32 s75, 0x7fff
	s_mov_b32 s76, 0xffff0000
	v_lshlrev_b32_e32 v42, 2, v22
	v_mov_b32_e32 v43, 0x7f800000
	v_mov_b32_e32 v44, 0x300
	v_lshlrev_b32_e32 v45, 2, v2
	s_mov_b32 s77, s57
	s_mov_b32 s98, s56
	s_cmpk_lt_i32 s57, 0x400
	s_cbranch_scc1 .LBB0_33
	s_cmpk_lt_i32 s57, 0x600
	s_cbranch_scc1 .Lp0_class_b
	s_sub_i32 s77, s57, 0x200
	s_movk_i32 s98, 0x200
	s_mov_b64 s[38:39], 0
	s_branch .LBB0_33
.Lp0_class_b:
	s_mov_b64 s[40:41], 0
	s_branch .LBB0_33
.LBB0_32:
	s_add_i32 s77, s77, s98
	s_mov_b64 s[38:39], -1
	s_add_i32 s58, s58, s59
	s_cmpk_gt_i32 s77, 0x7ff
	s_cbranch_scc1 .LBB0_54

; __device__ __forceinline__ unsigned cvtpk_s(float lo, float hi) { f32x2 v = {lo, hi}; bf16x2_t b = __builtin_convertvector(v, bf16x2_t); return __builtin_bit_cast(unsigned, b); }
; __global__ void __launch_bounds__(NWAVES * 64, 2) mk_fwd(Args args) {
;     ...
;             const int wm0 = NGW >= 2048 ? NGW - 64 : 0;
;             for (int bb = (args.sub == 11 ? -1 : gw - wm0); bb >= 0 && bb < 64; bb += NGW) {
;                 if (args.sub < 13) { const f32x4* wsrc = (const f32x4*)(args.in[5] + (size_t)bb * 2048) + lane;
;                     f32x4 wv[8];
; #pragma unroll
;                     for (int q = 0; q < 8; ++q) wv[q] = wsrc[64 * q];
; #pragma unroll
;                     for (int q = 0; q < 8; ++q) { const int e = (lane + 64 * q) * 4; const int i = ((bb & 7) * 16) + (e >> 7), j = e & 127; const bool keep = ((j >> 6) <= (i >> 6));
;                         u32x2 o; o.x = keep ? pg8::cvtpk_s(wv[q][0], wv[q][1]) : 0u; o.y = keep ? pg8::cvtpk_s(wv[q][2], wv[q][3]) : 0u;
;                         *(u32x2*)(WM + (size_t)bb * 2048 + e) = o; } }
.LBB0_54:
	s_sub_i32 s2, s56, 64
	s_cmpk_gt_i32 s33, 0xff
	s_movk_i32 s2, 0x400
	s_sub_i32 s12, s57, s2
	s_cmp_lt_u32 s12, 64
	s_cselect_b64 s[2:3], -1, 0
	s_and_b64 s[2:3], s[14:15], s[2:3]
	s_andn2_b64 vcc, exec, s[2:3]
	s_mov_b32 s5, 0
	s_cbranch_vccnz .LBB0_91
	s_cmp_lt_i32 s94, 13
	s_cselect_b64 s[2:3], -1, 0
	v_lshlrev_b32_e32 v34, 4, v194
	v_mov_b32_e32 v35, 0
	v_lshlrev_b32_e32 v2, 2, v194
	v_cndmask_b32_e64 v3, 0, 1, s[2:3]
	s_waitcnt lgkmcnt(0)
	v_readlane_b32 s16, v234, 22
	v_lshl_add_u64 v[36:37], s[46:47], 0, v[34:35]
	v_bfe_u32 v1, v0, 4, 1
	s_lshl_b32 s4, s12, 11
	s_lshl_b32 s13, s33, 14
	v_cmp_ne_u32_e64 s[2:3], 1, v3
	v_lshlrev_b32_e32 v34, 1, v2
	v_readlane_b32 s17, v234, 23
	s_branch .LBB0_58

; __global__ void __launch_bounds__(NWAVES * 64, 2) mk_fwd(Args args) {
	.amdhsa_kernel _Z6mk_fwd4Args
		.amdhsa_group_segment_fixed_size 0
		.amdhsa_private_segment_fixed_size 0
		.amdhsa_kernarg_size 480
		.amdhsa_user_sgpr_count 2
		.amdhsa_user_sgpr_dispatch_ptr 0
		.amdhsa_user_sgpr_queue_ptr 0
		.amdhsa_user_sgpr_kernarg_segment_ptr 1
		.amdhsa_user_sgpr_dispatch_id 0
		.amdhsa_user_sgpr_kernarg_preload_length 0
		.amdhsa_user_sgpr_kernarg_preload_offset 0
		.amdhsa_user_sgpr_private_segment_size 0
		.amdhsa_uses_dynamic_stack 0
		.amdhsa_enable_private_segment 0
		.amdhsa_system_sgpr_workgroup_id_x 1
		.amdhsa_system_sgpr_workgroup_id_y 0
		.amdhsa_system_sgpr_workgroup_id_z 0
		.amdhsa_system_sgpr_workgroup_info 0
		.amdhsa_system_vgpr_workitem_id 0
		.amdhsa_next_free_vgpr 235
		.amdhsa_next_free_sgpr 99
		.amdhsa_accum_offset 236
		.amdhsa_reserve_vcc 1
		.amdhsa_float_round_mode_32 0
		.amdhsa_float_round_mode_16_64 0
		.amdhsa_float_denorm_mode_32 3
		.amdhsa_float_denorm_mode_16_64 3
		.amdhsa_dx10_clamp 1
		.amdhsa_ieee_mode 1
		.amdhsa_fp16_overflow 0
		.amdhsa_tg_split 0
		.amdhsa_exception_fp_ieee_invalid_op 0
		.amdhsa_exception_fp_denorm_src 0
		.amdhsa_exception_fp_ieee_div_zero 0
		.amdhsa_exception_fp_ieee_overflow 0
		.amdhsa_exception_fp_ieee_underflow 0
		.amdhsa_exception_fp_ieee_inexact 0
		.amdhsa_exception_int_div_zero 0
	.end_amdhsa_kernel

; __global__ void __launch_bounds__(NWAVES * 64, 2) mk_fwd(Args args) {
amdhsa.kernels:
  - .agpr_count:     0
    .args:
      - .offset:         0
        .size:           224
        .value_kind:     by_value
      - .offset:         224
        .size:           4
        .value_kind:     hidden_block_count_x
      - .offset:         228
        .size:           4
        .value_kind:     hidden_block_count_y
      - .offset:         232
        .size:           4
        .value_kind:     hidden_block_count_z
      - .offset:         236
        .size:           2
        .value_kind:     hidden_group_size_x
      - .offset:         238
        .size:           2
        .value_kind:     hidden_group_size_y
      - .offset:         240
        .size:           2
        .value_kind:     hidden_group_size_z
      - .offset:         242
        .size:           2
        .value_kind:     hidden_remainder_x
      - .offset:         244
        .size:           2
        .value_kind:     hidden_remainder_y
      - .offset:         246
        .size:           2
        .value_kind:     hidden_remainder_z
      - .offset:         264
        .size:           8
        .value_kind:     hidden_global_offset_x
      - .offset:         272
        .size:           8
        .value_kind:     hidden_global_offset_y
      - .offset:         280
        .size:           8
        .value_kind:     hidden_global_offset_z
      - .offset:         288
        .size:           2
        .value_kind:     hidden_grid_dims
      - .offset:         344
        .size:           4
        .value_kind:     hidden_dynamic_lds_size
    .group_segment_fixed_size: 0
    .kernarg_segment_align: 8
    .kernarg_segment_size: 480
    .language:       OpenCL C
    .language_version:
      - 2
      - 0
    .max_flat_workgroup_size: 512
    .name:           _Z6mk_fwd4Args
    .private_segment_fixed_size: 0
    .sgpr_count:     105
    .sgpr_spill_count: 67
    .symbol:         _Z6mk_fwd4Args.kd
    .uniform_work_group_size: 1
    .uses_dynamic_stack: false
    .vgpr_count:     235
    .vgpr_spill_count: 0
    .wavefront_size: 64
